# diff-attention: second V half-tile DMA addressed by instruction offset 128 with M0 compensated (one 64-bit VALU add less per step)
# speedup vs baseline: 1.0100x; 1.0060x over previous
.LBB0_1126:
	s_lshl_b32 s4, s9, 1
	v_add_u32_e32 v216, s4, v247
	ds_read_b64_tr_b16 v[226:227], v216 offset:24576
	ds_read_b64_tr_b16 v[228:229], v216 offset:25088
	s_waitcnt lgkmcnt(9)
	v_mfma_f32_32x32x16_bf16 v[130:145], v[206:209], v[174:177], v[66:81]
	v_add_f32_e32 v1, v98, v99
	v_add_f32_e32 v1, v100, v1
	v_add_f32_e32 v1, v101, v1
	v_add_f32_e32 v1, v102, v1
	v_add_f32_e32 v1, v103, v1
	v_cvt_pk_bf16_f32 v158, v98, v99
	v_cvt_pk_bf16_f32 v159, v100, v101
	ds_read_b64_tr_b16 v[250:251], v216 offset:28672
	ds_read_b64_tr_b16 v[252:253], v216 offset:29184
	s_waitcnt lgkmcnt(10)
	v_mfma_f32_32x32x16_bf16 v[114:129], v[198:201], v[174:177], v[66:81]
	v_add_f32_e32 v1, v104, v1
	v_add_f32_e32 v1, v105, v1
	v_add_f32_e32 v1, v106, v1
	v_add_f32_e32 v1, v107, v1
	v_cvt_pk_bf16_f32 v160, v102, v103
	v_cvt_pk_bf16_f32 v161, v104, v105
	ds_read_b64_tr_b16 v[198:199], v216 offset:25600
	ds_read_b64_tr_b16 v[200:201], v216 offset:26112
	s_waitcnt lgkmcnt(11)
	v_mfma_f32_32x32x16_bf16 v[130:145], v[202:205], v[170:173], v[130:145]
	v_add_f32_e32 v1, v108, v1
	v_add_f32_e32 v1, v109, v1
	v_add_f32_e32 v1, v110, v1
	v_add_f32_e32 v1, v111, v1
	v_cvt_pk_bf16_f32 v154, v106, v107
	v_cvt_pk_bf16_f32 v155, v108, v109
	ds_read_b64_tr_b16 v[106:107], v216 offset:29696
	ds_read_b64_tr_b16 v[108:109], v216 offset:30208
	s_waitcnt lgkmcnt(12)
	v_mfma_f32_32x32x16_bf16 v[114:129], v[194:197], v[170:173], v[114:129]
	v_add_f32_e32 v1, v112, v1
	v_add_f32_e32 v1, v113, v1
	v_add_f32_e32 v1, v82, v1
	v_add_f32_e32 v1, v83, v1
	v_cvt_pk_bf16_f32 v156, v110, v111
	v_cvt_pk_bf16_f32 v157, v112, v113
	ds_read_b64_tr_b16 v[102:103], v216 offset:26624
	ds_read_b64_tr_b16 v[104:105], v216 offset:27136
	s_waitcnt lgkmcnt(13)
	v_mfma_f32_32x32x16_bf16 v[130:145], v[190:193], v[166:169], v[130:145]
	v_add_f32_e32 v1, v84, v1
	v_add_f32_e32 v1, v85, v1
	v_add_f32_e32 v1, v86, v1
	v_add_f32_e32 v1, v87, v1
	v_cvt_pk_bf16_f32 v150, v82, v83
	v_cvt_pk_bf16_f32 v151, v84, v85
	ds_read_b64_tr_b16 v[98:99], v216 offset:30720
	ds_read_b64_tr_b16 v[100:101], v216 offset:31232
	s_waitcnt lgkmcnt(14)
	v_mfma_f32_32x32x16_bf16 v[114:129], v[186:189], v[166:169], v[114:129]
	v_add_f32_e32 v1, v88, v1
	v_add_f32_e32 v1, v89, v1
	v_add_f32_e32 v1, v90, v1
	v_add_f32_e32 v1, v91, v1
	v_cvt_pk_bf16_f32 v152, v86, v87
	v_cvt_pk_bf16_f32 v153, v88, v89
	ds_read_b64_tr_b16 v[86:87], v216 offset:27648
	ds_read_b64_tr_b16 v[88:89], v216 offset:28160
	s_waitcnt lgkmcnt(14)
	v_mfma_f32_32x32x16_bf16 v[130:145], v[182:185], v[162:165], v[130:145]
	v_add_f32_e32 v1, v92, v1
	v_add_f32_e32 v1, v93, v1
	v_add_f32_e32 v1, v94, v1
	v_add_f32_e32 v1, v95, v1
	v_cvt_pk_bf16_f32 v146, v90, v91
	v_cvt_pk_bf16_f32 v147, v92, v93
	ds_read_b64_tr_b16 v[90:91], v216 offset:31744
	ds_read_b64_tr_b16 v[92:93], v216 offset:32256
	v_mfma_f32_32x32x16_bf16 v[114:129], v[178:181], v[162:165], v[114:129]
	v_add_f32_e32 v1, v96, v1
	v_add_f32_e32 v1, v97, v1
	v_cvt_pk_bf16_f32 v148, v94, v95
	v_cvt_pk_bf16_f32 v149, v96, v97
	s_add_i32 s4, s15, s55
	v_lshl_add_u64 v[82:83], v[212:213], 0, s[62:63]
	s_mov_b32 s8, m0
	s_mov_b32 m0, s4
	s_nop 0
	global_load_lds_dwordx4 v[82:83], off
	s_mov_b32 m0, s8
	s_lshl_b32 s4, s84, 1
	s_waitcnt lgkmcnt(14)
	v_mfma_f32_32x32x16_bf16 v[50:65], v[158:161], v[226:229], v[50:65]
	v_lshl_add_u64 v[82:83], v[214:215], 0, s[58:59]
	s_add_i32 s4, s4, s1
	s_mov_b32 s8, m0
	s_mov_b32 m0, s4
	s_nop 0
	global_load_lds_dwordx4 v[82:83], off
	s_mov_b32 m0, s8
	s_addk_i32 s4, 0x1f80
	s_mov_b32 s8, m0
	s_mov_b32 m0, s4
	s_nop 0
	global_load_lds_dwordx4 v[82:83], off offset:128
	s_mov_b32 m0, s8
	ds_read_b64_tr_b16 v[206:207], v216 offset:32768
	ds_read_b64_tr_b16 v[208:209], v216 offset:33280
	s_waitcnt lgkmcnt(14)
	v_mfma_f32_32x32x16_bf16 v[34:49], v[158:161], v[250:253], v[34:49]
	ds_read_b64_tr_b16 v[110:111], v216 offset:36864
	ds_read_b64_tr_b16 v[112:113], v216 offset:37376
	s_waitcnt lgkmcnt(14)
	v_mfma_f32_32x32x16_bf16 v[50:65], v[154:157], v[198:201], v[50:65]
	ds_read_b64_tr_b16 v[94:95], v216 offset:33792
	ds_read_b64_tr_b16 v[96:97], v216 offset:34304
	v_max_f32_e32 v82, v130, v131
	v_max3_f32 v83, v132, v133, v115
	v_max3_f32 v82, v82, v114, v116
	v_max3_f32 v82, v82, v117, v134
	v_max3_f32 v83, v83, v136, v137
	v_max3_f32 v82, v82, v135, v118
	v_max3_f32 v83, v83, v120, v121
	v_max3_f32 v82, v82, v119, v138
	v_max3_f32 v83, v83, v140, v141
	v_max3_f32 v82, v82, v139, v122
	v_max3_f32 v83, v83, v124, v125
	v_max3_f32 v82, v82, v123, v142
	v_max3_f32 v83, v83, v144, v145
	v_max3_f32 v82, v82, v143, v126
	v_max3_f32 v83, v83, v128, v129
	v_max3_f32 v82, v82, v127, v83
	v_cmp_lt_f32_e32 vcc, s13, v82
	s_cmp_lg_u64 vcc, 0
	v_add_f32_e32 v1, v249, v1
	s_cselect_b64 s[86:87], -1, 0
	s_cbranch_vccnz .LBB0_1134

.LBB0_1129:
	s_add_i32 s4, s84, 0x2000
	s_cmpk_lg_i32 s84, 0x4000
	s_cselect_b32 s4, s4, 0
	s_lshl_b32 s8, s15, 1
	v_add_u32_e32 v226, s8, v247
	ds_read_b64_tr_b16 v[206:207], v226 offset:24576
	ds_read_b64_tr_b16 v[208:209], v226 offset:25088
	v_mfma_f32_32x32x16_bf16 v[98:113], v[82:85], v[174:177], v[66:81]
	v_add_f32_e32 v86, v130, v131
	v_add_f32_e32 v86, v132, v86
	v_add_f32_e32 v86, v133, v86
	v_add_f32_e32 v86, v134, v86
	v_add_f32_e32 v86, v135, v86
	v_cvt_pk_bf16_f32 v158, v130, v131
	v_cvt_pk_bf16_f32 v159, v132, v133
	ds_read_b64_tr_b16 v[250:251], v226 offset:28672
	ds_read_b64_tr_b16 v[252:253], v226 offset:29184
	v_add_f32_e32 v82, v136, v86
	v_add_f32_e32 v82, v137, v82
	v_add_f32_e32 v82, v138, v82
	v_add_f32_e32 v130, v139, v82
	v_mfma_f32_32x32x16_bf16 v[82:97], v[198:201], v[174:177], v[66:81]
	v_cvt_pk_bf16_f32 v160, v134, v135
	v_cvt_pk_bf16_f32 v161, v136, v137
	ds_read_b64_tr_b16 v[198:199], v226 offset:25600
	ds_read_b64_tr_b16 v[200:201], v226 offset:26112
	v_mfma_f32_32x32x16_bf16 v[98:113], v[202:205], v[170:173], v[98:113]
	v_add_f32_e32 v130, v140, v130
	v_add_f32_e32 v130, v141, v130
	v_add_f32_e32 v130, v142, v130
	v_add_f32_e32 v130, v143, v130
	v_cvt_pk_bf16_f32 v154, v138, v139
	v_cvt_pk_bf16_f32 v155, v140, v141
	ds_read_b64_tr_b16 v[138:139], v226 offset:29696
	ds_read_b64_tr_b16 v[140:141], v226 offset:30208
	v_mfma_f32_32x32x16_bf16 v[82:97], v[190:193], v[170:173], v[82:97]
	v_add_f32_e32 v130, v144, v130
	v_add_f32_e32 v130, v145, v130
	v_add_f32_e32 v130, v114, v130
	v_add_f32_e32 v130, v115, v130
	v_cvt_pk_bf16_f32 v156, v142, v143
	v_cvt_pk_bf16_f32 v157, v144, v145
	ds_read_b64_tr_b16 v[134:135], v226 offset:26624
	ds_read_b64_tr_b16 v[136:137], v226 offset:27136
	v_mfma_f32_32x32x16_bf16 v[98:113], v[194:197], v[166:169], v[98:113]
	v_add_f32_e32 v130, v116, v130
	v_add_f32_e32 v130, v117, v130
	v_add_f32_e32 v130, v118, v130
	v_add_f32_e32 v142, v119, v130
	v_cvt_pk_bf16_f32 v150, v114, v115
	v_cvt_pk_bf16_f32 v151, v116, v117
	ds_read_b64_tr_b16 v[130:131], v226 offset:30720
	ds_read_b64_tr_b16 v[132:133], v226 offset:31232
	v_mfma_f32_32x32x16_bf16 v[82:97], v[182:185], v[166:169], v[82:97]
	v_add_f32_e32 v114, v120, v142
	v_add_f32_e32 v114, v121, v114
	v_add_f32_e32 v114, v122, v114
	v_add_f32_e32 v142, v123, v114
	v_cvt_pk_bf16_f32 v152, v118, v119
	v_cvt_pk_bf16_f32 v153, v120, v121
	ds_read_b64_tr_b16 v[114:115], v226 offset:27648
	ds_read_b64_tr_b16 v[116:117], v226 offset:28160
	v_mfma_f32_32x32x16_bf16 v[98:113], v[186:189], v[162:165], v[98:113]
	v_add_f32_e32 v118, v124, v142
	v_add_f32_e32 v118, v125, v118
	v_add_f32_e32 v118, v126, v118
	v_add_f32_e32 v142, v127, v118
	v_cvt_pk_bf16_f32 v146, v122, v123
	v_cvt_pk_bf16_f32 v147, v124, v125
	ds_read_b64_tr_b16 v[118:119], v226 offset:31744
	ds_read_b64_tr_b16 v[120:121], v226 offset:32256
	v_mfma_f32_32x32x16_bf16 v[82:97], v[178:181], v[162:165], v[82:97]
	v_add_f32_e32 v122, v128, v142
	v_add_f32_e32 v122, v129, v122
	v_add_f32_e32 v178, 0, v122
	v_cvt_pk_bf16_f32 v148, v126, v127
	v_cvt_pk_bf16_f32 v149, v128, v129
	s_mov_b64 s[8:9], 0x180000
	v_lshl_add_u64 v[122:123], v[212:213], 0, s[8:9]
	s_add_i32 s8, s84, s55
	s_mov_b32 s9, m0
	s_mov_b32 m0, s8
	s_nop 0
	global_load_lds_dwordx4 v[122:123], off
	s_mov_b32 m0, s9
	s_lshl_b32 s8, s4, 1
	s_waitcnt lgkmcnt(14)
	v_mfma_f32_32x32x16_bf16 v[50:65], v[158:161], v[206:209], v[50:65]
	v_lshl_add_u64 v[216:217], v[214:215], 0, s[60:61]
	s_add_i32 s8, s8, s1
	s_mov_b32 s9, m0
	s_mov_b32 m0, s8
	s_nop 0
	global_load_lds_dwordx4 v[216:217], off
	s_mov_b32 m0, s9
	s_addk_i32 s8, 0x1f80
	s_mov_b32 s9, m0
	s_mov_b32 m0, s8
	s_nop 0
	global_load_lds_dwordx4 v[216:217], off offset:128
	s_mov_b32 m0, s9
	ds_read_b64_tr_b16 v[142:143], v226 offset:32768
	ds_read_b64_tr_b16 v[144:145], v226 offset:33280
	s_waitcnt lgkmcnt(14)
	v_mfma_f32_32x32x16_bf16 v[34:49], v[158:161], v[250:253], v[34:49]
	ds_read_b64_tr_b16 v[126:127], v226 offset:36864
	ds_read_b64_tr_b16 v[128:129], v226 offset:37376
	s_waitcnt lgkmcnt(14)
	v_mfma_f32_32x32x16_bf16 v[50:65], v[154:157], v[198:201], v[50:65]
	ds_read_b64_tr_b16 v[122:123], v226 offset:33792
	ds_read_b64_tr_b16 v[124:125], v226 offset:34304
	v_max_f32_e32 v179, v98, v99
	v_max3_f32 v180, v100, v101, v83
	v_max3_f32 v179, v179, v82, v84
	v_max3_f32 v179, v179, v85, v102
	v_max3_f32 v180, v180, v104, v105
	v_max3_f32 v179, v179, v103, v86
	v_max3_f32 v180, v180, v88, v89
	v_max3_f32 v179, v179, v87, v106
	v_max3_f32 v180, v180, v108, v109
	v_max3_f32 v179, v179, v107, v90
	v_max3_f32 v180, v180, v92, v93
	v_max3_f32 v179, v179, v91, v110
	v_max3_f32 v180, v180, v112, v113
	v_max3_f32 v179, v179, v111, v94
	v_max3_f32 v180, v180, v96, v97
	v_add_f32_e32 v249, v1, v178
	v_max3_f32 v1, v179, v95, v180
	v_cmp_lt_f32_e32 vcc, s13, v1
	s_cmp_lg_u64 vcc, 0
	s_cselect_b64 s[86:87], -1, 0
	s_cbranch_vccnz .LBB0_1137

.LBB0_1143:
	v_lshl_add_u64 v[228:229], s[90:91], 1, v[224:225]
	s_lshl_b32 s33, s8, 1
	s_waitcnt lgkmcnt(14)
	v_mfma_f32_32x32x16_bf16 v[50:65], v[158:161], v[210:213], v[50:65]
	v_lshl_add_u64 v[82:83], v[228:229], 0, s[58:59]
	s_add_i32 s9, s33, s1
	s_mov_b32 s84, m0
	s_mov_b32 m0, s9
	s_nop 0
	global_load_lds_dwordx4 v[82:83], off
	s_mov_b32 m0, s84
	s_addk_i32 s9, 0x1f80
	s_mov_b32 s84, m0
	s_mov_b32 m0, s9
	s_nop 0
	global_load_lds_dwordx4 v[82:83], off offset:128
	s_mov_b32 m0, s84
	ds_read_b64_tr_b16 v[206:207], v250 offset:32768
	ds_read_b64_tr_b16 v[208:209], v250 offset:33280
	v_add_f32_e32 v1, v249, v1
	s_waitcnt lgkmcnt(14)
	v_mfma_f32_32x32x16_bf16 v[34:49], v[158:161], v[214:217], v[34:49]
	ds_read_b64_tr_b16 v[110:111], v250 offset:36864
	ds_read_b64_tr_b16 v[112:113], v250 offset:37376
	s_waitcnt lgkmcnt(14)
	v_mfma_f32_32x32x16_bf16 v[50:65], v[154:157], v[198:201], v[50:65]
	ds_read_b64_tr_b16 v[94:95], v250 offset:33792
	ds_read_b64_tr_b16 v[96:97], v250 offset:34304
	v_max_f32_e32 v82, v130, v131
	v_max3_f32 v83, v132, v133, v115
	v_max3_f32 v82, v82, v114, v116
	v_max3_f32 v82, v82, v117, v134
	v_max3_f32 v83, v83, v136, v137
	v_max3_f32 v82, v82, v135, v118
	v_max3_f32 v83, v83, v120, v121
	v_max3_f32 v82, v82, v119, v138
	v_max3_f32 v83, v83, v140, v141
	v_max3_f32 v82, v82, v139, v122
	v_max3_f32 v83, v83, v124, v125
	v_max3_f32 v82, v82, v123, v142
	v_max3_f32 v83, v83, v144, v145
	v_max3_f32 v82, v82, v143, v126
	v_max3_f32 v83, v83, v128, v129
	v_max3_f32 v82, v82, v127, v83
	v_mov_b32_e32 v83, v82
	s_nop 1
	v_permlane32_swap_b32_e32 v82, v83
	v_max_f32_e32 v82, v82, v83
	v_cmp_lt_f32_e32 vcc, s13, v82
	s_cmp_lg_u64 vcc, 0
	s_cselect_b64 s[92:93], -1, 0
	s_cbranch_vccnz .LBB0_1161

.LBB0_1150:
	s_add_i32 s4, s8, 0x2000
	s_cmpk_lg_i32 s8, 0x4000
	s_cselect_b32 s4, s4, 0
	s_lshl_b32 s84, s4, 1
	s_waitcnt lgkmcnt(14)
	v_mfma_f32_32x32x16_bf16 v[50:65], v[158:161], v[206:209], v[50:65]
	s_add_i32 s9, s84, s1
	v_lshl_add_u64 v[124:125], v[228:229], 0, s[60:61]
	s_mov_b32 s90, m0
	s_mov_b32 m0, s9
	s_nop 0
	global_load_lds_dwordx4 v[124:125], off
	s_mov_b32 m0, s90
	v_add_f32_e32 v249, v1, v122
	s_addk_i32 s9, 0x1f80
	s_mov_b32 s90, m0
	s_mov_b32 m0, s9
	s_nop 0
	global_load_lds_dwordx4 v[124:125], off offset:128
	s_mov_b32 m0, s90
	ds_read_b64_tr_b16 v[142:143], v214 offset:32768
	ds_read_b64_tr_b16 v[144:145], v214 offset:33280
	s_waitcnt lgkmcnt(14)
	v_mfma_f32_32x32x16_bf16 v[34:49], v[158:161], v[210:213], v[34:49]
	ds_read_b64_tr_b16 v[126:127], v214 offset:36864
	ds_read_b64_tr_b16 v[128:129], v214 offset:37376
	s_waitcnt lgkmcnt(14)
	v_mfma_f32_32x32x16_bf16 v[50:65], v[154:157], v[198:201], v[50:65]
	ds_read_b64_tr_b16 v[122:123], v214 offset:33792
	ds_read_b64_tr_b16 v[124:125], v214 offset:34304
	v_max_f32_e32 v1, v98, v99
	v_max3_f32 v178, v100, v101, v83
	v_max3_f32 v1, v1, v82, v84
	v_max3_f32 v1, v1, v85, v102
	v_max3_f32 v178, v178, v104, v105
	v_max3_f32 v1, v1, v103, v86
	v_max3_f32 v178, v178, v88, v89
	v_max3_f32 v1, v1, v87, v106
	v_max3_f32 v178, v178, v108, v109
	v_max3_f32 v1, v1, v107, v90
	v_max3_f32 v178, v178, v92, v93
	v_max3_f32 v1, v1, v91, v110
	v_max3_f32 v178, v178, v112, v113
	v_max3_f32 v1, v1, v111, v94
	v_max3_f32 v178, v178, v96, v97
	v_max3_f32 v1, v1, v95, v178
	v_mov_b32_e32 v178, v1
	s_nop 1
	v_permlane32_swap_b32_e32 v1, v178
	v_max_f32_e32 v1, v1, v178
	v_cmp_lt_f32_e32 vcc, s13, v1
	s_cmp_lg_u64 vcc, 0
	s_cselect_b64 s[90:91], -1, 0
	s_cbranch_vccnz .LBB0_1164
